# v09 + the last XCD leader no longer publishes the release generation word (nobody reads it): no atomic ack to wait for before its acquire
# speedup vs baseline: 1.0000x; 1.0000x over previous
.LBB0_216:
	s_or_b64 exec, exec, s[8:9]
	s_waitcnt vmcnt(0)
	v_readfirstlane_b32 s4, v2
	v_cvt_f32_u32_e32 v2, v0
	v_sub_u32_e32 v3, 0, v0
	v_add_u32_e32 v1, s4, v1
	v_readlane_b32 s4, v242, 44
	v_rcp_iflag_f32_e32 v2, v2
	v_readlane_b32 s5, v242, 45
	s_mov_b64 s[8:9], 0
	v_mul_f32_e32 v2, 0x4f7ffffe, v2
	v_cvt_u32_f32_e32 v2, v2
	v_mul_lo_u32 v3, v3, v2
	v_mul_hi_u32 v3, v2, v3
	v_add_u32_e32 v2, v2, v3
	v_mul_hi_u32 v2, v1, v2
	v_mul_lo_u32 v3, v2, v0
	v_sub_u32_e32 v3, v1, v3
	v_cmp_ge_u32_e32 vcc, v3, v0
	v_add_u32_e32 v4, 1, v2
	v_add_u32_e32 v1, 1, v1
	v_cndmask_b32_e32 v2, v2, v4, vcc
	v_sub_u32_e32 v4, v3, v0
	v_cndmask_b32_e32 v3, v3, v4, vcc
	v_cmp_ge_u32_e32 vcc, v3, v0
	v_add_u32_e32 v3, 1, v2
	s_nop 0
	v_cndmask_b32_e32 v2, v2, v3, vcc
	v_mul_lo_u32 v3, v0, v2
	v_add_u32_e32 v0, v3, v0
	v_cmp_ne_u32_e32 vcc, v1, v0
	v_mov_b32_e32 v3, v0
	v_mov_b64_e32 v[0:1], s[4:5]
	s_and_saveexec_b64 s[4:5], vcc
	s_cbranch_execz .LBB0_228
	v_readlane_b32 s8, v242, 42
	v_readlane_b32 s9, v242, 43
	s_mov_b64 s[38:39], 0
	s_nop 3
	global_load_dword v0, v173, s[8:9] sc1
	s_waitcnt vmcnt(0)
	v_sub_u32_e32 v0, v0, v3
	v_cmp_gt_i32_e32 vcc, 0, v0
	s_and_saveexec_b64 s[8:9], vcc
	s_cbranch_execz .LBB0_227
	s_mov_b32 s11, 1
	s_branch .LBB0_220

.LBB0_756:
	s_or_b64 exec, exec, s[8:9]
	s_waitcnt vmcnt(0)
	v_readfirstlane_b32 s4, v2
	v_cvt_f32_u32_e32 v2, v0
	v_sub_u32_e32 v3, 0, v0
	v_add_u32_e32 v1, s4, v1
	v_readlane_b32 s4, v242, 44
	v_rcp_iflag_f32_e32 v2, v2
	v_readlane_b32 s5, v242, 45
	s_mov_b64 s[8:9], 0
	v_mul_f32_e32 v2, 0x4f7ffffe, v2
	v_cvt_u32_f32_e32 v2, v2
	v_mul_lo_u32 v3, v3, v2
	v_mul_hi_u32 v3, v2, v3
	v_add_u32_e32 v2, v2, v3
	v_mul_hi_u32 v2, v1, v2
	v_mul_lo_u32 v3, v2, v0
	v_sub_u32_e32 v3, v1, v3
	v_cmp_ge_u32_e32 vcc, v3, v0
	v_add_u32_e32 v4, 1, v2
	v_add_u32_e32 v1, 1, v1
	v_cndmask_b32_e32 v2, v2, v4, vcc
	v_sub_u32_e32 v4, v3, v0
	v_cndmask_b32_e32 v3, v3, v4, vcc
	v_cmp_ge_u32_e32 vcc, v3, v0
	v_add_u32_e32 v3, 1, v2
	s_nop 0
	v_cndmask_b32_e32 v2, v2, v3, vcc
	v_mul_lo_u32 v3, v0, v2
	v_add_u32_e32 v0, v3, v0
	v_cmp_ne_u32_e32 vcc, v1, v0
	v_mov_b32_e32 v3, v0
	v_mov_b64_e32 v[0:1], s[4:5]
	s_and_saveexec_b64 s[4:5], vcc
	s_cbranch_execz .LBB0_768
	v_readlane_b32 s8, v242, 42
	v_readlane_b32 s9, v242, 43
	s_mov_b64 s[28:29], 0
	s_nop 3
	global_load_dword v0, v173, s[8:9] sc1
	s_waitcnt vmcnt(0)
	v_sub_u32_e32 v0, v0, v3
	v_cmp_gt_i32_e32 vcc, 0, v0
	s_and_saveexec_b64 s[8:9], vcc
	s_cbranch_execz .LBB0_767
	s_mov_b32 s11, 1
	s_branch .LBB0_760

.LBB0_1067:
	s_or_b64 exec, exec, s[8:9]
	s_waitcnt vmcnt(0)
	v_readfirstlane_b32 s4, v2
	v_cvt_f32_u32_e32 v2, v0
	v_sub_u32_e32 v3, 0, v0
	v_add_u32_e32 v1, s4, v1
	v_readlane_b32 s4, v242, 44
	v_rcp_iflag_f32_e32 v2, v2
	v_readlane_b32 s5, v242, 45
	s_mov_b64 s[8:9], 0
	v_mul_f32_e32 v2, 0x4f7ffffe, v2
	v_cvt_u32_f32_e32 v2, v2
	v_mul_lo_u32 v3, v3, v2
	v_mul_hi_u32 v3, v2, v3
	v_add_u32_e32 v2, v2, v3
	v_mul_hi_u32 v2, v1, v2
	v_mul_lo_u32 v3, v2, v0
	v_sub_u32_e32 v3, v1, v3
	v_cmp_ge_u32_e32 vcc, v3, v0
	v_add_u32_e32 v4, 1, v2
	v_add_u32_e32 v1, 1, v1
	v_cndmask_b32_e32 v2, v2, v4, vcc
	v_sub_u32_e32 v4, v3, v0
	v_cndmask_b32_e32 v3, v3, v4, vcc
	v_cmp_ge_u32_e32 vcc, v3, v0
	v_add_u32_e32 v3, 1, v2
	s_nop 0
	v_cndmask_b32_e32 v2, v2, v3, vcc
	v_mul_lo_u32 v3, v0, v2
	v_add_u32_e32 v0, v3, v0
	v_cmp_ne_u32_e32 vcc, v1, v0
	v_mov_b32_e32 v3, v0
	v_mov_b64_e32 v[0:1], s[4:5]
	s_and_saveexec_b64 s[4:5], vcc
	s_cbranch_execz .LBB0_1079
	v_readlane_b32 s8, v242, 42
	v_readlane_b32 s9, v242, 43
	s_mov_b64 s[28:29], 0
	s_nop 3
	global_load_dword v0, v173, s[8:9] sc1
	s_waitcnt vmcnt(0)
	v_sub_u32_e32 v0, v0, v3
	v_cmp_gt_i32_e32 vcc, 0, v0
	s_and_saveexec_b64 s[8:9], vcc
	s_cbranch_execz .LBB0_1078
	s_mov_b32 s26, 1
	s_branch .LBB0_1071

.LBB0_1124:
	s_or_b64 exec, exec, s[8:9]
	s_waitcnt vmcnt(0)
	v_readfirstlane_b32 s4, v2
	v_cvt_f32_u32_e32 v2, v0
	v_sub_u32_e32 v3, 0, v0
	v_add_u32_e32 v1, s4, v1
	v_readlane_b32 s4, v242, 44
	v_rcp_iflag_f32_e32 v2, v2
	v_readlane_b32 s5, v242, 45
	s_mov_b64 s[8:9], 0
	v_mul_f32_e32 v2, 0x4f7ffffe, v2
	v_cvt_u32_f32_e32 v2, v2
	v_mul_lo_u32 v3, v3, v2
	v_mul_hi_u32 v3, v2, v3
	v_add_u32_e32 v2, v2, v3
	v_mul_hi_u32 v2, v1, v2
	v_mul_lo_u32 v3, v2, v0
	v_sub_u32_e32 v3, v1, v3
	v_cmp_ge_u32_e32 vcc, v3, v0
	v_add_u32_e32 v4, 1, v2
	v_add_u32_e32 v1, 1, v1
	v_cndmask_b32_e32 v2, v2, v4, vcc
	v_sub_u32_e32 v4, v3, v0
	v_cndmask_b32_e32 v3, v3, v4, vcc
	v_cmp_ge_u32_e32 vcc, v3, v0
	v_add_u32_e32 v3, 1, v2
	s_nop 0
	v_cndmask_b32_e32 v2, v2, v3, vcc
	v_mul_lo_u32 v3, v0, v2
	v_add_u32_e32 v0, v3, v0
	v_cmp_ne_u32_e32 vcc, v1, v0
	v_mov_b32_e32 v3, v0
	v_mov_b64_e32 v[0:1], s[4:5]
	s_and_saveexec_b64 s[4:5], vcc
	s_cbranch_execz .LBB0_1136
	v_readlane_b32 s8, v242, 42
	v_readlane_b32 s9, v242, 43
	s_mov_b64 s[38:39], 0
	s_nop 3
	global_load_dword v0, v173, s[8:9] sc1
	s_waitcnt vmcnt(0)
	v_sub_u32_e32 v0, v0, v3
	v_cmp_gt_i32_e32 vcc, 0, v0
	s_and_saveexec_b64 s[8:9], vcc
	s_cbranch_execz .LBB0_1135
	s_mov_b32 s26, 1
	s_branch .LBB0_1128

.LBB0_1196:
	s_or_b64 exec, exec, s[8:9]
	s_waitcnt vmcnt(0)
	v_readfirstlane_b32 s4, v2
	v_cvt_f32_u32_e32 v2, v0
	v_sub_u32_e32 v3, 0, v0
	v_add_u32_e32 v1, s4, v1
	v_readlane_b32 s4, v242, 44
	v_rcp_iflag_f32_e32 v2, v2
	v_readlane_b32 s5, v242, 45
	s_mov_b64 s[8:9], 0
	v_mul_f32_e32 v2, 0x4f7ffffe, v2
	v_cvt_u32_f32_e32 v2, v2
	v_mul_lo_u32 v3, v3, v2
	v_mul_hi_u32 v3, v2, v3
	v_add_u32_e32 v2, v2, v3
	v_mul_hi_u32 v2, v1, v2
	v_mul_lo_u32 v3, v2, v0
	v_sub_u32_e32 v3, v1, v3
	v_cmp_ge_u32_e32 vcc, v3, v0
	v_add_u32_e32 v4, 1, v2
	v_add_u32_e32 v1, 1, v1
	v_cndmask_b32_e32 v2, v2, v4, vcc
	v_sub_u32_e32 v4, v3, v0
	v_cndmask_b32_e32 v3, v3, v4, vcc
	v_cmp_ge_u32_e32 vcc, v3, v0
	v_add_u32_e32 v3, 1, v2
	s_nop 0
	v_cndmask_b32_e32 v2, v2, v3, vcc
	v_mul_lo_u32 v3, v0, v2
	v_add_u32_e32 v0, v3, v0
	v_cmp_ne_u32_e32 vcc, v1, v0
	v_mov_b32_e32 v3, v0
	v_mov_b64_e32 v[0:1], s[4:5]
	s_and_saveexec_b64 s[4:5], vcc
	s_cbranch_execz .LBB0_1208
	v_readlane_b32 s8, v242, 42
	v_readlane_b32 s9, v242, 43
	s_mov_b64 s[42:43], 0
	s_nop 3
	global_load_dword v0, v173, s[8:9] sc1
	s_waitcnt vmcnt(0)
	v_sub_u32_e32 v0, v0, v3
	v_cmp_gt_i32_e32 vcc, 0, v0
	s_and_saveexec_b64 s[8:9], vcc
	s_cbranch_execz .LBB0_1207
	s_mov_b32 s26, 1
	s_branch .LBB0_1200

.LBB0_1382:
	s_or_b64 exec, exec, s[8:9]
	s_waitcnt vmcnt(0)
	v_readfirstlane_b32 s4, v2
	v_cvt_f32_u32_e32 v2, v0
	v_sub_u32_e32 v3, 0, v0
	v_add_u32_e32 v1, s4, v1
	v_readlane_b32 s4, v242, 44
	v_rcp_iflag_f32_e32 v2, v2
	v_readlane_b32 s5, v242, 45
	s_mov_b64 s[8:9], 0
	v_mul_f32_e32 v2, 0x4f7ffffe, v2
	v_cvt_u32_f32_e32 v2, v2
	v_mul_lo_u32 v3, v3, v2
	v_mul_hi_u32 v3, v2, v3
	v_add_u32_e32 v2, v2, v3
	v_mul_hi_u32 v2, v1, v2
	v_mul_lo_u32 v3, v2, v0
	v_sub_u32_e32 v3, v1, v3
	v_cmp_ge_u32_e32 vcc, v3, v0
	v_add_u32_e32 v4, 1, v2
	v_add_u32_e32 v1, 1, v1
	v_cndmask_b32_e32 v2, v2, v4, vcc
	v_sub_u32_e32 v4, v3, v0
	v_cndmask_b32_e32 v3, v3, v4, vcc
	v_cmp_ge_u32_e32 vcc, v3, v0
	v_add_u32_e32 v3, 1, v2
	s_nop 0
	v_cndmask_b32_e32 v2, v2, v3, vcc
	v_mul_lo_u32 v3, v0, v2
	v_add_u32_e32 v0, v3, v0
	v_cmp_ne_u32_e32 vcc, v1, v0
	v_mov_b32_e32 v3, v0
	v_mov_b64_e32 v[0:1], s[4:5]
	s_and_saveexec_b64 s[4:5], vcc
	s_cbranch_execz .LBB0_1394
	v_readlane_b32 s8, v242, 42
	v_readlane_b32 s9, v242, 43
	s_mov_b64 s[40:41], 0
	s_nop 3
	global_load_dword v0, v173, s[8:9] sc1
	s_waitcnt vmcnt(0)
	v_sub_u32_e32 v0, v0, v3
	v_cmp_gt_i32_e32 vcc, 0, v0
	s_and_saveexec_b64 s[8:9], vcc
	s_cbranch_execz .LBB0_1393
	s_mov_b32 s26, 1
	s_branch .LBB0_1386
